# c12 plus per-group rotation of the Q/K/V/G column-block order in the two projection GEMMs
# baseline (speedup 1.0000x reference)
.LBB0_304:
	s_ashr_i32 s2, s5, 3
	s_add_i32 s2, s7, s2
	s_ashr_i32 s3, s2, 31
	s_lshr_b32 s3, s3, 25
	s_add_i32 s3, s2, s3
	s_ashr_i32 s5, s3, 7
	s_and_b32 s3, s3, 0xffffff80
	s_sub_i32 s2, s2, s3
	s_bfe_i32 s3, s2, 0x80000
	s_bfe_u32 s3, s3, 0x2000d
	s_add_i32 s3, s2, s3
	s_bfe_i32 s6, s3, 0x80000
	s_and_b32 s3, s3, 0xfc
	s_sub_i32 s2, s2, s3
	s_lshl_b32 s5, s5, 2
	s_sext_i32_i16 s6, s6
	s_sext_i32_i8 s2, s2
	s_add_i32 s34, s5, s2
	s_ashr_i32 s8, s6, 2
	s_and_b32 s99, s69, 3
	s_lshl_b32 s99, s99, 3
	s_add_i32 s8, s8, s99
	s_and_b32 s8, s8, 31

.LBB0_317:
	s_and_b32 s99, s69, 3
	s_lshl_b32 s99, s99, 3
	s_add_i32 s24, s24, s99
	s_and_b32 s24, s24, 31
	s_ashr_i32 s27, s26, 31
	s_lshl_b64 s[28:29], s[26:27], 20
	s_add_u32 s28, s42, s28
	s_addc_u32 s29, s43, s29
	s_and_b64 s[30:31], s[4:5], exec
	s_cselect_b32 s9, s29, s7
	s_cselect_b32 s27, s28, s6
	s_ashr_i32 s25, s24, 31
	s_lshl_b64 s[30:31], s[24:25], 20
	s_add_u32 s30, s44, s30
	s_addc_u32 s31, s45, s31
	s_and_b64 s[38:39], s[4:5], exec
	s_cselect_b32 s25, s31, s37
	s_cselect_b32 s62, s30, s36
	s_ashr_i32 s35, s34, 31
	s_lshl_b64 s[38:39], s[34:35], 13
	s_add_u32 s35, s36, 0x100
	v_mov_b32_e32 v0, 0
	v_mov_b32_e32 v179, v178
	v_mov_b32_e32 v178, v191
	v_mov_b32_e32 v191, v190
	v_mov_b32_e32 v190, v185
	v_mov_b32_e32 v185, v215
	v_mov_b32_e32 v203, v214
	v_lshl_add_u64 v[128:129], v[164:165], 0, s[38:39]
	v_lshl_add_u64 v[130:131], s[6:7], 0, v[170:171]
	s_nop 0
	v_lshl_add_u64 v[132:133], s[6:7], 0, v[172:173]
	s_addc_u32 s63, s37, 0
	s_mov_b32 s64, -2
	s_mov_b64 s[36:37], 0
	v_mov_b32_e32 v1, v0
	v_mov_b32_e32 v2, v0
	v_mov_b32_e32 v3, v0
	v_mov_b32_e32 v4, v0
	v_mov_b32_e32 v5, v0
	v_mov_b32_e32 v6, v0
	v_mov_b32_e32 v7, v0
	v_mov_b32_e32 v8, v0
	v_mov_b32_e32 v9, v0
	v_mov_b32_e32 v10, v0
	v_mov_b32_e32 v11, v0
	v_mov_b32_e32 v12, v0
	v_mov_b32_e32 v13, v0
	v_mov_b32_e32 v14, v0
	v_mov_b32_e32 v15, v0
	v_mov_b32_e32 v20, v0
	v_mov_b32_e32 v21, v0
	v_mov_b32_e32 v22, v0
	v_mov_b32_e32 v23, v0
	v_mov_b32_e32 v24, v0
	v_mov_b32_e32 v25, v0
	v_mov_b32_e32 v26, v0
	v_mov_b32_e32 v27, v0
	v_mov_b32_e32 v36, v0
	v_mov_b32_e32 v37, v0
	v_mov_b32_e32 v38, v0
	v_mov_b32_e32 v39, v0
	v_mov_b32_e32 v40, v0
	v_mov_b32_e32 v41, v0
	v_mov_b32_e32 v42, v0
	v_mov_b32_e32 v43, v0
	v_mov_b32_e32 v112, v0
	v_mov_b32_e32 v113, v0
	v_mov_b32_e32 v114, v0
	v_mov_b32_e32 v115, v0
	v_mov_b32_e32 v116, v0
	v_mov_b32_e32 v117, v0
	v_mov_b32_e32 v118, v0
	v_mov_b32_e32 v119, v0
	v_mov_b32_e32 v16, v0
	v_mov_b32_e32 v17, v0
	v_mov_b32_e32 v18, v0
	v_mov_b32_e32 v19, v0
	v_mov_b32_e32 v28, v0
	v_mov_b32_e32 v29, v0
	v_mov_b32_e32 v30, v0
	v_mov_b32_e32 v31, v0
	v_mov_b32_e32 v32, v0
	v_mov_b32_e32 v33, v0
	v_mov_b32_e32 v34, v0
	v_mov_b32_e32 v35, v0
	v_mov_b32_e32 v44, v0
	v_mov_b32_e32 v45, v0
	v_mov_b32_e32 v46, v0
	v_mov_b32_e32 v47, v0
	v_mov_b32_e32 v48, v0
	v_mov_b32_e32 v49, v0
	v_mov_b32_e32 v50, v0
	v_mov_b32_e32 v51, v0
	v_mov_b32_e32 v52, v0
	v_mov_b32_e32 v53, v0
	v_mov_b32_e32 v54, v0
	v_mov_b32_e32 v55, v0
	v_mov_b32_e32 v56, v0
	v_mov_b32_e32 v57, v0
	v_mov_b32_e32 v58, v0
	v_mov_b32_e32 v59, v0
	v_mov_b32_e32 v60, v0
	v_mov_b32_e32 v61, v0
	v_mov_b32_e32 v62, v0
	v_mov_b32_e32 v63, v0
	v_mov_b32_e32 v68, v0
	v_mov_b32_e32 v69, v0
	v_mov_b32_e32 v70, v0
	v_mov_b32_e32 v71, v0
	v_mov_b32_e32 v72, v0
	v_mov_b32_e32 v73, v0
	v_mov_b32_e32 v74, v0
	v_mov_b32_e32 v75, v0
	v_mov_b32_e32 v84, v0
	v_mov_b32_e32 v85, v0
	v_mov_b32_e32 v86, v0
	v_mov_b32_e32 v87, v0
	v_mov_b32_e32 v88, v0
	v_mov_b32_e32 v89, v0
	v_mov_b32_e32 v90, v0
	v_mov_b32_e32 v91, v0
	v_mov_b32_e32 v100, v0
	v_mov_b32_e32 v101, v0
	v_mov_b32_e32 v102, v0
	v_mov_b32_e32 v103, v0
	v_mov_b32_e32 v104, v0
	v_mov_b32_e32 v105, v0
	v_mov_b32_e32 v106, v0
	v_mov_b32_e32 v107, v0
	v_mov_b32_e32 v64, v0
	v_mov_b32_e32 v65, v0
	v_mov_b32_e32 v66, v0
	v_mov_b32_e32 v67, v0
	v_mov_b32_e32 v76, v0
	v_mov_b32_e32 v77, v0
	v_mov_b32_e32 v78, v0
	v_mov_b32_e32 v79, v0
	v_mov_b32_e32 v80, v0
	v_mov_b32_e32 v81, v0
	v_mov_b32_e32 v82, v0
	v_mov_b32_e32 v83, v0
	v_mov_b32_e32 v92, v0
	v_mov_b32_e32 v93, v0
	v_mov_b32_e32 v94, v0
	v_mov_b32_e32 v95, v0
	v_mov_b32_e32 v96, v0
	v_mov_b32_e32 v97, v0
	v_mov_b32_e32 v98, v0
	v_mov_b32_e32 v99, v0
	v_mov_b32_e32 v108, v0
	v_mov_b32_e32 v109, v0
	v_mov_b32_e32 v110, v0
	v_mov_b32_e32 v111, v0
	v_mov_b32_e32 v120, v0
	v_mov_b32_e32 v121, v0
	v_mov_b32_e32 v122, v0
	v_mov_b32_e32 v123, v0
	v_mov_b32_e32 v124, v0
	v_mov_b32_e32 v125, v0
	v_mov_b32_e32 v126, v0
	v_mov_b32_e32 v127, v0
	s_branch .LBB0_319

.LBB0_1009:
	s_ashr_i32 s2, s4, 3
	s_add_i32 s2, s6, s2
	s_ashr_i32 s3, s2, 31
	s_lshr_b32 s3, s3, 25
	s_add_i32 s3, s2, s3
	s_ashr_i32 s4, s3, 7
	s_and_b32 s3, s3, 0xffffff80
	s_sub_i32 s2, s2, s3
	s_bfe_i32 s3, s2, 0x80000
	s_bfe_u32 s3, s3, 0x2000d
	s_add_i32 s3, s2, s3
	s_bfe_i32 s5, s3, 0x80000
	s_and_b32 s3, s3, 0xfc
	s_sub_i32 s2, s2, s3
	s_lshl_b32 s4, s4, 2
	s_sext_i32_i16 s5, s5
	s_sext_i32_i8 s2, s2
	s_add_i32 s22, s4, s2
	s_ashr_i32 s24, s5, 2
	s_and_b32 s99, s69, 3
	s_lshl_b32 s99, s99, 3
	s_add_i32 s24, s24, s99
	s_and_b32 s24, s24, 31
	s_andn2_b64 vcc, exec, s[0:1]
	s_cbranch_vccnz .LBB0_1004

.LBB0_1021:
	s_and_b32 s99, s69, 3
	s_lshl_b32 s99, s99, 3
	s_add_i32 s14, s14, s99
	s_and_b32 s14, s14, 31
	s_ashr_i32 s17, s16, 31
	s_lshl_b64 s[18:19], s[16:17], 20
	s_add_u32 s18, s33, s18
	s_addc_u32 s19, s34, s19
	s_and_b64 s[20:21], s[2:3], exec
	s_cselect_b32 s17, s19, s5
	s_cselect_b32 s52, s18, s4
	s_ashr_i32 s15, s14, 31
	s_lshl_b64 s[20:21], s[14:15], 20
	s_add_u32 s20, s37, s20
	s_addc_u32 s21, s38, s21
	s_and_b64 s[28:29], s[2:3], exec
	s_cselect_b32 s15, s21, s27
	s_cselect_b32 s53, s20, s26
	s_ashr_i32 s23, s22, 31
	s_lshl_b64 s[28:29], s[22:23], 13
	s_add_u32 s23, s26, 0x100
	v_mov_b32_e32 v4, 0
	v_lshl_add_u64 v[120:121], v[148:149], 0, s[28:29]
	v_lshl_add_u64 v[122:123], s[4:5], 0, v[150:151]
	v_lshl_add_u64 v[124:125], s[4:5], 0, v[152:153]
	s_addc_u32 s54, s27, 0
	s_mov_b32 s55, -2
	s_mov_b64 s[26:27], 0
	v_mov_b32_e32 v5, v4
	v_mov_b32_e32 v6, v4
	v_mov_b32_e32 v7, v4
	v_mov_b32_e32 v0, v4
	v_mov_b32_e32 v1, v4
	v_mov_b32_e32 v2, v4
	v_mov_b32_e32 v3, v4
	v_mov_b32_e32 v8, v4
	v_mov_b32_e32 v9, v4
	v_mov_b32_e32 v10, v4
	v_mov_b32_e32 v11, v4
	v_mov_b32_e32 v12, v4
	v_mov_b32_e32 v13, v4
	v_mov_b32_e32 v14, v4
	v_mov_b32_e32 v15, v4
	v_mov_b32_e32 v20, v4
	v_mov_b32_e32 v21, v4
	v_mov_b32_e32 v22, v4
	v_mov_b32_e32 v23, v4
	v_mov_b32_e32 v24, v4
	v_mov_b32_e32 v25, v4
	v_mov_b32_e32 v26, v4
	v_mov_b32_e32 v27, v4
	v_mov_b32_e32 v36, v4
	v_mov_b32_e32 v37, v4
	v_mov_b32_e32 v38, v4
	v_mov_b32_e32 v39, v4
	v_mov_b32_e32 v40, v4
	v_mov_b32_e32 v41, v4
	v_mov_b32_e32 v42, v4
	v_mov_b32_e32 v43, v4
	v_mov_b32_e32 v128, v4
	v_mov_b32_e32 v129, v4
	v_mov_b32_e32 v130, v4
	v_mov_b32_e32 v131, v4
	v_mov_b32_e32 v132, v4
	v_mov_b32_e32 v133, v4
	v_mov_b32_e32 v134, v4
	v_mov_b32_e32 v135, v4
	v_mov_b32_e32 v16, v4
	v_mov_b32_e32 v17, v4
	v_mov_b32_e32 v18, v4
	v_mov_b32_e32 v19, v4
	v_mov_b32_e32 v32, v4
	v_mov_b32_e32 v33, v4
	v_mov_b32_e32 v34, v4
	v_mov_b32_e32 v35, v4
	v_mov_b32_e32 v28, v4
	v_mov_b32_e32 v29, v4
	v_mov_b32_e32 v30, v4
	v_mov_b32_e32 v31, v4
	v_mov_b32_e32 v48, v4
	v_mov_b32_e32 v49, v4
	v_mov_b32_e32 v50, v4
	v_mov_b32_e32 v51, v4
	v_mov_b32_e32 v44, v4
	v_mov_b32_e32 v45, v4
	v_mov_b32_e32 v46, v4
	v_mov_b32_e32 v47, v4
	v_mov_b32_e32 v52, v4
	v_mov_b32_e32 v53, v4
	v_mov_b32_e32 v54, v4
	v_mov_b32_e32 v55, v4
	v_mov_b32_e32 v56, v4
	v_mov_b32_e32 v57, v4
	v_mov_b32_e32 v58, v4
	v_mov_b32_e32 v59, v4
	v_mov_b32_e32 v60, v4
	v_mov_b32_e32 v61, v4
	v_mov_b32_e32 v62, v4
	v_mov_b32_e32 v63, v4
	v_mov_b32_e32 v68, v4
	v_mov_b32_e32 v69, v4
	v_mov_b32_e32 v70, v4
	v_mov_b32_e32 v71, v4
	v_mov_b32_e32 v72, v4
	v_mov_b32_e32 v73, v4
	v_mov_b32_e32 v74, v4
	v_mov_b32_e32 v75, v4
	v_mov_b32_e32 v84, v4
	v_mov_b32_e32 v85, v4
	v_mov_b32_e32 v86, v4
	v_mov_b32_e32 v87, v4
	v_mov_b32_e32 v88, v4
	v_mov_b32_e32 v89, v4
	v_mov_b32_e32 v90, v4
	v_mov_b32_e32 v91, v4
	v_mov_b32_e32 v100, v4
	v_mov_b32_e32 v101, v4
	v_mov_b32_e32 v102, v4
	v_mov_b32_e32 v103, v4
	v_mov_b32_e32 v104, v4
	v_mov_b32_e32 v105, v4
	v_mov_b32_e32 v106, v4
	v_mov_b32_e32 v107, v4
	v_mov_b32_e32 v64, v4
	v_mov_b32_e32 v65, v4
	v_mov_b32_e32 v66, v4
	v_mov_b32_e32 v67, v4
	v_mov_b32_e32 v80, v4
	v_mov_b32_e32 v81, v4
	v_mov_b32_e32 v82, v4
	v_mov_b32_e32 v83, v4
	v_mov_b32_e32 v76, v4
	v_mov_b32_e32 v77, v4
	v_mov_b32_e32 v78, v4
	v_mov_b32_e32 v79, v4
	v_mov_b32_e32 v96, v4
	v_mov_b32_e32 v97, v4
	v_mov_b32_e32 v98, v4
	v_mov_b32_e32 v99, v4
	v_mov_b32_e32 v92, v4
	v_mov_b32_e32 v93, v4
	v_mov_b32_e32 v94, v4
	v_mov_b32_e32 v95, v4
	v_mov_b32_e32 v112, v4
	v_mov_b32_e32 v113, v4
	v_mov_b32_e32 v114, v4
	v_mov_b32_e32 v115, v4
	v_mov_b32_e32 v108, v4
	v_mov_b32_e32 v109, v4
	v_mov_b32_e32 v110, v4
	v_mov_b32_e32 v111, v4
	v_mov_b32_e32 v116, v4
	v_mov_b32_e32 v117, v4
	v_mov_b32_e32 v118, v4
	v_mov_b32_e32 v119, v4
	s_branch .LBB0_1023
